# gla_inter: wait for the o_intra reload deferred to just before the O stores (prefetch latency hidden behind the state-update MFMAs)
# baseline (speedup 1.0000x reference)
.LBB0_442:
	s_add_i32 s16, s18, -1
	s_and_b64 s[14:15], s[2:3], exec
	s_cselect_b32 s14, s16, s34
	s_add_i32 s14, s14, s13
	s_ashr_i32 s15, s14, 31
	s_lshl_b64 s[14:15], s[14:15], 18
	v_lshl_add_u64 v[70:71], v[142:143], 0, s[14:15]
	v_lshl_add_u64 v[150:151], v[70:71], 0, v[140:141]
	v_lshl_add_u64 v[144:145], v[70:71], 0, v[134:135]
	v_lshl_add_u64 v[146:147], v[70:71], 0, v[136:137]
	v_lshl_add_u64 v[148:149], v[70:71], 0, v[138:139]
	global_load_ushort v184, v[150:151], off
	global_load_ushort v181, v[144:145], off
	global_load_ushort v180, v[144:145], off offset:32
	global_load_ushort v182, v[146:147], off
	global_load_ushort v179, v[146:147], off offset:32
	global_load_ushort v183, v[148:149], off
	global_load_ushort v178, v[148:149], off offset:32
	global_load_ushort v177, v[150:151], off offset:32
	s_add_i32 s18, s18, 1
	s_cmp_eq_u32 s19, -1
	ds_read_b128 v[186:189], v130 offset:33792
	ds_read_b128 v[190:193], v167
	ds_read_b128 v[194:197], v168
	ds_read_b128 v[198:201], v130 offset:33856
	ds_read_b128 v[202:205], v167 offset:64
	ds_read_b128 v[206:209], v168 offset:64
	ds_read_b128 v[210:213], v130 offset:33920
	ds_read_b128 v[214:217], v167 offset:128
	ds_read_b128 v[218:221], v168 offset:128
	ds_read_b128 v[234:237], v130 offset:33984
	ds_read_b128 v[238:241], v167 offset:192
	ds_read_b128 v[242:245], v168 offset:192
	s_waitcnt lgkmcnt(9)
	v_mfma_f32_16x16x32_bf16 v[74:77], v[186:189], v[190:193], 0
	v_mfma_f32_16x16x32_bf16 v[70:73], v[186:189], v[194:197], 0
	ds_read_b128 v[186:189], v130 offset:34048
	ds_read_b128 v[190:193], v167 offset:256
	ds_read_b128 v[194:197], v168 offset:256
	s_waitcnt lgkmcnt(9)
	v_mfma_f32_16x16x32_bf16 v[74:77], v[198:201], v[202:205], v[74:77]
	v_mfma_f32_16x16x32_bf16 v[70:73], v[198:201], v[206:209], v[70:73]
	ds_read_b128 v[198:201], v130 offset:34112
	ds_read_b128 v[202:205], v167 offset:320
	ds_read_b128 v[206:209], v168 offset:320
	s_waitcnt lgkmcnt(9)
	v_mfma_f32_16x16x32_bf16 v[74:77], v[210:213], v[214:217], v[74:77]
	v_mfma_f32_16x16x32_bf16 v[70:73], v[210:213], v[218:221], v[70:73]
	ds_read_b128 v[210:213], v130 offset:34176
	ds_read_b128 v[214:217], v167 offset:384
	ds_read_b128 v[218:221], v168 offset:384
	s_waitcnt lgkmcnt(9)
	v_mfma_f32_16x16x32_bf16 v[74:77], v[234:237], v[238:241], v[74:77]
	v_mfma_f32_16x16x32_bf16 v[70:73], v[234:237], v[242:245], v[70:73]
	s_waitcnt lgkmcnt(6)
	v_mfma_f32_16x16x32_bf16 v[74:77], v[186:189], v[190:193], v[74:77]
	v_mfma_f32_16x16x32_bf16 v[70:73], v[186:189], v[194:197], v[70:73]
	s_waitcnt lgkmcnt(3)
	v_mfma_f32_16x16x32_bf16 v[74:77], v[198:201], v[202:205], v[74:77]
	v_mfma_f32_16x16x32_bf16 v[70:73], v[198:201], v[206:209], v[70:73]
	s_waitcnt lgkmcnt(0)
	v_mfma_f32_16x16x32_bf16 v[74:77], v[210:213], v[214:217], v[74:77]
	v_mfma_f32_16x16x32_bf16 v[70:73], v[210:213], v[218:221], v[70:73]
	ds_read_b128 v[78:81], v130 offset:34240
	ds_read_b128 v[82:85], v167 offset:448
	ds_read_b128 v[86:89], v169
	s_waitcnt lgkmcnt(0)
	v_pk_mul_f32 v[96:97], v[40:41], v[88:89]
	v_mfma_f32_16x16x32_bf16 v[74:77], v[78:81], v[82:85], v[74:77]
	ds_read_b128 v[82:85], v168 offset:448
	v_pk_mul_f32 v[94:95], v[38:39], v[86:87]
	v_pk_mul_f32 v[40:41], v[64:65], v[88:89]
	s_waitcnt lgkmcnt(0)
	v_mfma_f32_16x16x32_bf16 v[70:73], v[78:81], v[82:85], v[70:73]
	v_mul_f32_e64 v84, v48, v88
	v_mul_f32_e64 v85, v49, v89
	v_pk_mul_f32 v[82:83], v[46:47], v[86:87]
	ds_read_b128 v[46:49], v169 offset:64
	v_pk_mul_f32 v[80:81], v[52:53], v[88:89]
	v_pk_mul_f32 v[78:79], v[50:51], v[86:87]
	v_pk_mul_f32 v[38:39], v[62:63], v[86:87]
	s_nop 0
	s_waitcnt lgkmcnt(0)
	v_pk_mul_f32 v[52:53], v[44:45], v[48:49]
	v_pk_mul_f32 v[50:51], v[42:43], v[46:47]
	v_pk_mul_f32 v[92:93], v[56:57], v[48:49]
	v_pk_mul_f32 v[90:91], v[54:55], v[46:47]
	v_pk_mul_f32 v[88:89], v[60:61], v[48:49]
	v_pk_mul_f32 v[86:87], v[58:59], v[46:47]
	v_pk_mul_f32 v[44:45], v[68:69], v[48:49]
	v_pk_mul_f32 v[42:43], v[66:67], v[46:47]
	ds_read_u16 v46, v171 offset:528
	ds_read_u16 v47, v171 offset:1056
	ds_read_u16 v48, v171 offset:1584
	ds_read_u16 v49, v171 offset:2112
	ds_read_u16 v58, v171 offset:2640
	ds_read_u16 v59, v171 offset:3168
	ds_read_u16 v60, v170
	ds_read_u16 v61, v170 offset:32
	ds_read_u16 v62, v171
	ds_read_u16 v66, v171 offset:32
	ds_read_u16 v67, v171 offset:560
	ds_read_u16 v156, v171 offset:1088
	ds_read_u16 v68, v171 offset:1616
	ds_read_u16 v157, v171 offset:2144
	ds_read_u16 v69, v171 offset:2672
	ds_read_u16 v158, v171 offset:3200
	ds_read_u16 v54, v173 offset:144
	ds_read_u16 v55, v173 offset:288
	ds_read_u16 v56, v173 offset:432
	ds_read_u16 v63, v173 offset:576
	ds_read_u16 v57, v173 offset:720
	ds_read_u16 v64, v173 offset:864
	s_waitcnt lgkmcnt(4)
	v_perm_b32 v55, v55, v54, s74
	v_perm_b32 v65, v59, v58, s74
	s_waitcnt lgkmcnt(2)
	v_perm_b32 v56, v63, v56, s74
	ds_read_u16 v54, v172
	ds_read_u16 v159, v172 offset:32
	ds_read_u16 v63, v173
	ds_read_u16 v185, v173 offset:32
	s_waitcnt lgkmcnt(4)
	v_perm_b32 v57, v64, v57, s74
	v_perm_b32 v64, v49, v48, s74
	v_perm_b32 v62, v62, v60, s74
	s_waitcnt lgkmcnt(1)
	v_perm_b32 v54, v63, v54, s74
	v_perm_b32 v63, v47, v46, s74
	v_perm_b32 v69, v158, v69, s74
	v_perm_b32 v68, v157, v68, s74
	v_perm_b32 v67, v156, v67, s74
	v_perm_b32 v66, v66, v61, s74
	v_mfma_f32_16x16x32_bf16 v[46:49], v[62:65], v[54:57], v[94:97]
	s_nop 1
	v_mfma_f32_16x16x32_bf16 v[50:53], v[66:69], v[54:57], v[50:53]
	ds_read_u16 v54, v173 offset:176
	ds_read_u16 v55, v173 offset:320
	ds_read_u16 v56, v173 offset:464
	ds_read_u16 v57, v173 offset:608
	ds_read_u16 v58, v173 offset:752
	ds_read_u16 v59, v173 offset:896
	s_waitcnt lgkmcnt(2)
	v_perm_b32 v60, v57, v56, s74
	s_waitcnt lgkmcnt(0)
	v_perm_b32 v61, v59, v58, s74
	v_perm_b32 v59, v55, v54, s74
	v_perm_b32 v58, v185, v159, s74
	s_nop 1
	v_mfma_f32_16x16x32_bf16 v[54:57], v[62:65], v[58:61], v[82:85]
	v_mfma_f32_16x16x32_bf16 v[58:61], v[66:69], v[58:61], v[90:93]
	s_nop 1
	ds_read_u16 v82, v172 offset:64
	ds_read_u16 v90, v173 offset:64
	ds_read_u16 v83, v173 offset:208
	ds_read_u16 v91, v173 offset:352
	ds_read_u16 v84, v173 offset:496
	ds_read_u16 v92, v173 offset:640
	ds_read_u16 v85, v173 offset:784
	ds_read_u16 v93, v173 offset:928
	s_waitcnt lgkmcnt(4)
	v_perm_b32 v83, v91, v83, s74
	v_perm_b32 v82, v90, v82, s74
	s_waitcnt lgkmcnt(2)
	v_perm_b32 v84, v92, v84, s74
	s_waitcnt lgkmcnt(0)
	v_perm_b32 v85, v93, v85, s74
	s_nop 1
	v_mfma_f32_16x16x32_bf16 v[78:81], v[62:65], v[82:85], v[78:81]
	v_mfma_f32_16x16x32_bf16 v[82:85], v[66:69], v[82:85], v[86:89]
	s_nop 2
	ds_read_u16 v86, v172 offset:96
	ds_read_u16 v90, v173 offset:96
	ds_read_u16 v87, v173 offset:240
	ds_read_u16 v91, v173 offset:384
	ds_read_u16 v88, v173 offset:528
	ds_read_u16 v92, v173 offset:672
	ds_read_u16 v89, v173 offset:816
	ds_read_u16 v93, v173 offset:960
	s_waitcnt lgkmcnt(4)
	v_perm_b32 v87, v91, v87, s74
	v_perm_b32 v86, v90, v86, s74
	s_waitcnt lgkmcnt(2)
	v_perm_b32 v88, v92, v88, s74
	s_waitcnt lgkmcnt(0)
	v_perm_b32 v89, v93, v89, s74
	s_nop 1
	v_mfma_f32_16x16x32_bf16 v[62:65], v[62:65], v[86:89], v[38:41]
	v_mfma_f32_16x16x32_bf16 v[66:69], v[66:69], v[86:89], v[42:45]
	s_nop 1
	ds_read_u16 v38, v174 offset:528
	ds_read_u16 v39, v174 offset:1056
	ds_read_u16 v40, v174 offset:1584
	ds_read_u16 v41, v174 offset:2112
	ds_read_u16 v86, v174 offset:2640
	ds_read_u16 v87, v174 offset:3168
	ds_read_u16 v88, v174 offset:3696
	ds_read_u16 v89, v174
	ds_read_u16 v94, v174 offset:32
	ds_read_u16 v95, v174 offset:560
	ds_read_u16 v96, v174 offset:1088
	ds_read_u16 v97, v174 offset:1616
	ds_read_u16 v156, v174 offset:2144
	ds_read_u16 v157, v174 offset:2672
	ds_read_u16 v158, v174 offset:3200
	ds_read_u16 v159, v174 offset:3728
	ds_read_u16 v42, v175 offset:144
	ds_read_u16 v43, v175 offset:288
	ds_read_u16 v90, v175 offset:432
	ds_read_u16 v44, v175 offset:576
	ds_read_u16 v91, v175 offset:720
	ds_read_u16 v45, v175 offset:864
	ds_read_u16 v92, v175 offset:1008
	s_waitcnt lgkmcnt(4)
	v_perm_b32 v43, v90, v43, s74
	ds_read_u16 v90, v175
	ds_read_u16 v185, v175 offset:32
	s_waitcnt lgkmcnt(4)
	v_perm_b32 v44, v91, v44, s74
	v_perm_b32 v93, v88, v87, s74
	s_waitcnt lgkmcnt(2)
	v_perm_b32 v45, v92, v45, s74
	s_waitcnt lgkmcnt(1)
	v_perm_b32 v42, v42, v90, s74
	v_perm_b32 v92, v86, v41, s74
	v_perm_b32 v91, v40, v39, s74
	v_perm_b32 v90, v38, v89, s74
	v_perm_b32 v89, v159, v158, s74
	v_perm_b32 v88, v157, v156, s74
	v_perm_b32 v87, v97, v96, s74
	v_perm_b32 v86, v95, v94, s74
	v_mfma_f32_16x16x32_bf16 v[38:41], v[90:93], v[42:45], v[46:49]
	s_nop 0
	v_mfma_f32_16x16x32_bf16 v[42:45], v[86:89], v[42:45], v[50:53]
	s_nop 0
	ds_read_u16 v46, v175 offset:176
	ds_read_u16 v47, v175 offset:320
	ds_read_u16 v48, v175 offset:464
	ds_read_u16 v49, v175 offset:608
	ds_read_u16 v50, v175 offset:752
	ds_read_u16 v51, v175 offset:896
	ds_read_u16 v52, v175 offset:1040
	s_waitcnt lgkmcnt(0)
	v_perm_b32 v53, v52, v51, s74
	v_perm_b32 v52, v50, v49, s74
	v_perm_b32 v51, v48, v47, s74
	v_perm_b32 v50, v46, v185, s74
	s_nop 1
	v_mfma_f32_16x16x32_bf16 v[46:49], v[90:93], v[50:53], v[54:57]
	v_mfma_f32_16x16x32_bf16 v[54:57], v[86:89], v[50:53], v[58:61]
	ds_read_u16 v50, v175 offset:64
	ds_read_u16 v51, v175 offset:208
	ds_read_u16 v52, v175 offset:352
	ds_read_u16 v53, v175 offset:496
	ds_read_u16 v58, v175 offset:640
	ds_read_u16 v59, v175 offset:784
	ds_read_u16 v60, v175 offset:928
	ds_read_u16 v61, v175 offset:1072
	s_waitcnt lgkmcnt(0)
	v_perm_b32 v61, v61, v60, s74
	v_perm_b32 v60, v59, v58, s74
	v_perm_b32 v59, v53, v52, s74
	v_perm_b32 v58, v51, v50, s74
	s_nop 1
	v_mfma_f32_16x16x32_bf16 v[50:53], v[90:93], v[58:61], v[78:81]
	v_mfma_f32_16x16x32_bf16 v[58:61], v[86:89], v[58:61], v[82:85]
	s_nop 1
	ds_read_u16 v78, v175 offset:96
	ds_read_u16 v82, v175 offset:240
	ds_read_u16 v79, v175 offset:384
	ds_read_u16 v83, v175 offset:528
	ds_read_u16 v80, v175 offset:672
	ds_read_u16 v84, v175 offset:816
	ds_read_u16 v81, v175 offset:960
	ds_read_u16 v85, v175 offset:1104
	s_waitcnt vmcnt(0)
	v_lshlrev_b32_e32 v180, 16, v180
	v_lshlrev_b32_e32 v181, 16, v181
	v_lshlrev_b32_e32 v179, 16, v179
	v_lshlrev_b32_e32 v182, 16, v182
	v_lshlrev_b32_e32 v178, 16, v178
	v_lshlrev_b32_e32 v183, 16, v183
	v_lshlrev_b32_e32 v177, 16, v177
	v_lshlrev_b32_e32 v184, 16, v184
	v_add_f32_e32 v70, v70, v180
	v_add_f32_e32 v74, v74, v181
	v_cvt_pk_bf16_f32 v70, v70, v33
	v_cvt_pk_bf16_f32 v74, v74, v33
	global_store_short v[144:145], v70, off offset:32
	v_add_f32_e32 v70, v71, v179
	global_store_short v[144:145], v74, off
	v_add_f32_e32 v74, v75, v182
	v_cvt_pk_bf16_f32 v70, v70, v33
	v_cvt_pk_bf16_f32 v74, v74, v33
	global_store_short v[146:147], v70, off offset:32
	v_add_f32_e32 v70, v72, v178
	global_store_short v[146:147], v74, off
	v_add_f32_e32 v74, v76, v183
	v_cvt_pk_bf16_f32 v70, v70, v33
	s_waitcnt lgkmcnt(0)
	v_perm_b32 v81, v85, v81, s74
	v_perm_b32 v80, v84, v80, s74
	v_perm_b32 v79, v83, v79, s74
	v_perm_b32 v78, v82, v78, s74
	v_cvt_pk_bf16_f32 v74, v74, v33
	global_store_short v[148:149], v70, off offset:32
	v_add_f32_e32 v70, v73, v177
	v_mfma_f32_16x16x32_bf16 v[62:65], v[90:93], v[78:81], v[62:65]
	global_store_short v[148:149], v74, off
	v_add_f32_e32 v74, v77, v184
	v_cvt_pk_bf16_f32 v70, v70, v33
	v_mfma_f32_16x16x32_bf16 v[66:69], v[86:89], v[78:81], v[66:69]
	v_cvt_pk_bf16_f32 v78, v42, v43
	v_cvt_pk_bf16_f32 v74, v74, v33
	global_store_short v[150:151], v74, off
	global_store_short v[150:151], v70, off offset:32
	s_waitcnt lgkmcnt(0)
	s_barrier
	v_cvt_pk_bf16_f32 v70, v38, v39
	v_cvt_pk_bf16_f32 v71, v40, v41
	v_cvt_pk_bf16_f32 v72, v46, v47
	v_cvt_pk_bf16_f32 v79, v44, v45
	ds_write2_b64 v176, v[70:71], v[78:79] offset1:4
	v_add_u32_e32 v78, 0x2000, v176
	v_cvt_pk_bf16_f32 v73, v48, v49
	v_cvt_pk_bf16_f32 v70, v54, v55
	v_cvt_pk_bf16_f32 v71, v56, v57
	ds_write2_b64 v78, v[72:73], v[70:71] offset0:32 offset1:36
	v_add_u32_e32 v72, 0x4000, v176
	v_cvt_pk_bf16_f32 v74, v50, v51
	v_cvt_pk_bf16_f32 v75, v52, v53
	v_cvt_pk_bf16_f32 v70, v58, v59
	v_cvt_pk_bf16_f32 v71, v60, v61
	ds_write2_b64 v72, v[74:75], v[70:71] offset0:64 offset1:68
	v_add_u32_e32 v72, 0x6000, v176
	v_cvt_pk_bf16_f32 v76, v62, v63
	v_cvt_pk_bf16_f32 v77, v64, v65
	v_cvt_pk_bf16_f32 v70, v66, v67
	v_cvt_pk_bf16_f32 v71, v68, v69
	ds_write2_b64 v72, v[76:77], v[70:71] offset0:96 offset1:100
	s_waitcnt lgkmcnt(0)
	s_barrier
	s_cbranch_scc1 .LBB0_444
	s_mov_b32 s34, s19
	s_branch .LBB0_434
